# attention job epilogue both layers: scaled output tile staged through LDS so each lane does 16-byte gate loads and 16-byte stores (8+8 per lane) instead of 64+64 two-byte accesses; plus next-LRU-tile
# speedup vs baseline: 1.0046x; 1.0046x over previous
.LBB0_595:
	s_or_b64 exec, exec, s[2:3]
	v_readlane_b32 s68, v254, 12
	s_lshl_b64 s[2:3], s[8:9], 13
	v_readlane_b32 s76, v254, 20
	v_readlane_b32 s77, v254, 21
	s_add_u32 s2, s76, s2
	s_addc_u32 s3, s77, s3
	s_add_u32 s2, s2, s20
	s_addc_u32 s3, s3, s21
	s_lshl_b32 s4, s12, 8
	s_add_u32 s2, s2, s4
	v_readlane_b32 s74, v254, 18
	s_addc_u32 s3, s3, 0
	s_mul_i32 s6, s8, 0x5040
	v_readlane_b32 s75, v254, 19
	s_mul_hi_u32 s5, s8, 0x5040
	s_add_u32 s6, s74, s6
	s_addc_u32 s5, s75, s5
	s_add_u32 s6, s6, s14
	s_addc_u32 s5, s5, s15
	s_waitcnt lgkmcnt(0)
	v_add_u32_e32 v76, v179, v176
	v_mov_b32_e32 v80, v180
	s_add_u32 s4, s6, s4
	ds_read_b128 v[64:67], v76
	ds_read_b128 v[68:71], v76 offset:32
	ds_read_b128 v[72:75], v76 offset:64
	ds_read_b128 v[76:79], v76 offset:96
	s_addc_u32 s5, s5, 0
	v_and_b32_e32 v81, 31, v80
	v_bfe_u32 v82, v80, 5, 1
	v_lshrrev_b32_e32 v83, 6, v80
	v_and_b32_e32 v84, 63, v80
	v_lshrrev_b32_e32 v92, 1, v84
	v_and_b32_e32 v93, 1, v84
	v_lshl_add_u32 v94, v83, 5, v92
	v_mov_b64_e32 v[88:89], s[4:5]
	v_mad_i64_i32 v[88:89], s[6:7], v94, s84, v[88:89]
	v_lshlrev_b32_e32 v86, 6, v93
	v_mov_b32_e32 v87, 0
	v_lshl_add_u64 v[88:89], v[88:89], 0, v[86:87]
	global_load_dwordx4 v[128:131], v[88:89], off offset:0
	global_load_dwordx4 v[132:135], v[88:89], off offset:16
	global_load_dwordx4 v[136:139], v[88:89], off offset:32
	global_load_dwordx4 v[140:143], v[88:89], off offset:48
	global_load_dwordx4 v[144:147], v[88:89], off offset:128
	global_load_dwordx4 v[148:151], v[88:89], off offset:144
	global_load_dwordx4 v[152:155], v[88:89], off offset:160
	global_load_dwordx4 v[156:159], v[88:89], off offset:176
	v_mov_b32_e32 v95, 0
	v_lshlrev_b64 v[90:91], 13, v[94:95]
	v_lshl_add_u64 v[90:91], v[90:91], 0, s[2:3]
	v_lshl_add_u64 v[90:91], v[90:91], 0, v[86:87]
	v_mul_u32_u24_e32 v85, 0x2200, v83
	v_mul_u32_u24_e32 v86, 0x110, v92
	v_lshl_add_u32 v86, v93, 7, v86
	v_add_u32_e32 v86, v85, v86
	v_mul_u32_u24_e32 v87, 0x440, v82
	v_lshl_add_u32 v87, v81, 2, v87
	v_add_u32_e32 v85, v85, v87
	s_waitcnt lgkmcnt(0)
	v_rcp_f32_e32 v64, v64
	v_rcp_f32_e32 v65, v65
	v_rcp_f32_e32 v66, v66
	v_rcp_f32_e32 v67, v67
	v_rcp_f32_e32 v68, v68
	v_rcp_f32_e32 v69, v69
	v_rcp_f32_e32 v70, v70
	v_rcp_f32_e32 v71, v71
	v_rcp_f32_e32 v72, v72
	v_rcp_f32_e32 v73, v73
	v_rcp_f32_e32 v74, v74
	v_rcp_f32_e32 v75, v75
	v_rcp_f32_e32 v76, v76
	v_rcp_f32_e32 v77, v77
	v_rcp_f32_e32 v78, v78
	v_rcp_f32_e32 v79, v79
	v_mul_f32_e32 v0, v0, v64
	v_mul_f32_e32 v1, v1, v65
	v_mul_f32_e32 v2, v2, v66
	v_mul_f32_e32 v3, v3, v67
	v_mul_f32_e32 v4, v4, v68
	v_mul_f32_e32 v5, v5, v69
	v_mul_f32_e32 v6, v6, v70
	v_mul_f32_e32 v7, v7, v71
	v_mul_f32_e32 v8, v8, v72
	v_mul_f32_e32 v9, v9, v73
	v_mul_f32_e32 v10, v10, v74
	v_mul_f32_e32 v11, v11, v75
	v_mul_f32_e32 v12, v12, v76
	v_mul_f32_e32 v13, v13, v77
	v_mul_f32_e32 v14, v14, v78
	v_mul_f32_e32 v15, v15, v79
	v_mul_f32_e32 v16, v16, v64
	v_mul_f32_e32 v17, v17, v65
	v_mul_f32_e32 v18, v18, v66
	v_mul_f32_e32 v19, v19, v67
	v_mul_f32_e32 v20, v20, v68
	v_mul_f32_e32 v21, v21, v69
	v_mul_f32_e32 v22, v22, v70
	v_mul_f32_e32 v23, v23, v71
	v_mul_f32_e32 v24, v24, v72
	v_mul_f32_e32 v25, v25, v73
	v_mul_f32_e32 v26, v26, v74
	v_mul_f32_e32 v27, v27, v75
	v_mul_f32_e32 v28, v28, v76
	v_mul_f32_e32 v29, v29, v77
	v_mul_f32_e32 v30, v30, v78
	v_mul_f32_e32 v31, v31, v79
	v_mul_f32_e32 v32, v32, v64
	v_mul_f32_e32 v33, v33, v65
	v_mul_f32_e32 v34, v34, v66
	v_mul_f32_e32 v35, v35, v67
	v_mul_f32_e32 v36, v36, v68
	v_mul_f32_e32 v37, v37, v69
	v_mul_f32_e32 v38, v38, v70
	v_mul_f32_e32 v39, v39, v71
	v_mul_f32_e32 v40, v40, v72
	v_mul_f32_e32 v41, v41, v73
	v_mul_f32_e32 v42, v42, v74
	v_mul_f32_e32 v43, v43, v75
	v_mul_f32_e32 v44, v44, v76
	v_mul_f32_e32 v45, v45, v77
	v_mul_f32_e32 v46, v46, v78
	v_mul_f32_e32 v47, v47, v79
	v_mul_f32_e32 v48, v48, v64
	v_mul_f32_e32 v49, v49, v65
	v_mul_f32_e32 v50, v50, v66
	v_mul_f32_e32 v51, v51, v67
	v_mul_f32_e32 v52, v52, v68
	v_mul_f32_e32 v53, v53, v69
	v_mul_f32_e32 v54, v54, v70
	v_mul_f32_e32 v55, v55, v71
	v_mul_f32_e32 v56, v56, v72
	v_mul_f32_e32 v57, v57, v73
	v_mul_f32_e32 v58, v58, v74
	v_mul_f32_e32 v59, v59, v75
	v_mul_f32_e32 v60, v60, v76
	v_mul_f32_e32 v61, v61, v77
	v_mul_f32_e32 v62, v62, v78
	v_mul_f32_e32 v63, v63, v79
	s_barrier
	ds_write_b32 v85, v48
	ds_write_b32 v85, v49 offset:272
	ds_write_b32 v85, v50 offset:544
	ds_write_b32 v85, v51 offset:816
	ds_write_b32 v85, v52 offset:2176
	ds_write_b32 v85, v53 offset:2448
	ds_write_b32 v85, v54 offset:2720
	ds_write_b32 v85, v55 offset:2992
	ds_write_b32 v85, v56 offset:4352
	ds_write_b32 v85, v57 offset:4624
	ds_write_b32 v85, v58 offset:4896
	ds_write_b32 v85, v59 offset:5168
	ds_write_b32 v85, v60 offset:6528
	ds_write_b32 v85, v61 offset:6800
	ds_write_b32 v85, v62 offset:7072
	ds_write_b32 v85, v63 offset:7344
	ds_write_b32 v85, v32 offset:128
	ds_write_b32 v85, v33 offset:400
	ds_write_b32 v85, v34 offset:672
	ds_write_b32 v85, v35 offset:944
	ds_write_b32 v85, v36 offset:2304
	ds_write_b32 v85, v37 offset:2576
	ds_write_b32 v85, v38 offset:2848
	ds_write_b32 v85, v39 offset:3120
	ds_write_b32 v85, v40 offset:4480
	ds_write_b32 v85, v41 offset:4752
	ds_write_b32 v85, v42 offset:5024
	ds_write_b32 v85, v43 offset:5296
	ds_write_b32 v85, v44 offset:6656
	ds_write_b32 v85, v45 offset:6928
	ds_write_b32 v85, v46 offset:7200
	ds_write_b32 v85, v47 offset:7472
	s_waitcnt lgkmcnt(0)
	ds_read_b128 v[96:99], v86
	ds_read_b128 v[100:103], v86 offset:16
	ds_read_b128 v[104:107], v86 offset:32
	ds_read_b128 v[108:111], v86 offset:48
	ds_read_b128 v[112:115], v86 offset:64
	ds_read_b128 v[116:119], v86 offset:80
	ds_read_b128 v[120:123], v86 offset:96
	ds_read_b128 v[124:127], v86 offset:112
	s_waitcnt vmcnt(4) lgkmcnt(0)
	v_lshlrev_b32_e32 v186, 16, v128
	v_and_b32_e32 v187, 0xffff0000, v128
	v_lshlrev_b32_e32 v188, 16, v129
	v_and_b32_e32 v189, 0xffff0000, v129
	v_mul_f32_e32 v224, 0xbfb8aa3b, v186
	v_mul_f32_e32 v225, 0xbfb8aa3b, v187
	v_mul_f32_e32 v226, 0xbfb8aa3b, v188
	v_mul_f32_e32 v227, 0xbfb8aa3b, v189
	v_exp_f32_e32 v224, v224
	v_exp_f32_e32 v225, v225
	v_exp_f32_e32 v226, v226
	v_exp_f32_e32 v227, v227
	v_add_f32_e32 v224, 1.0, v224
	v_add_f32_e32 v225, 1.0, v225
	v_add_f32_e32 v226, 1.0, v226
	v_add_f32_e32 v227, 1.0, v227
	v_rcp_f32_e32 v224, v224
	v_rcp_f32_e32 v225, v225
	v_rcp_f32_e32 v226, v226
	v_rcp_f32_e32 v227, v227
	v_mul_f32_e32 v186, v224, v186
	v_mul_f32_e32 v187, v225, v187
	v_mul_f32_e32 v188, v226, v188
	v_mul_f32_e32 v189, v227, v189
	v_mul_f32_e32 v186, v96, v186
	v_mul_f32_e32 v187, v97, v187
	v_mul_f32_e32 v188, v98, v188
	v_mul_f32_e32 v189, v99, v189
	v_lshlrev_b32_e32 v190, 16, v130
	v_and_b32_e32 v191, 0xffff0000, v130
	v_lshlrev_b32_e32 v192, 16, v131
	v_and_b32_e32 v193, 0xffff0000, v131
	v_mul_f32_e32 v224, 0xbfb8aa3b, v190
	v_mul_f32_e32 v225, 0xbfb8aa3b, v191
	v_mul_f32_e32 v226, 0xbfb8aa3b, v192
	v_mul_f32_e32 v227, 0xbfb8aa3b, v193
	v_exp_f32_e32 v224, v224
	v_exp_f32_e32 v225, v225
	v_exp_f32_e32 v226, v226
	v_exp_f32_e32 v227, v227
	v_add_f32_e32 v224, 1.0, v224
	v_add_f32_e32 v225, 1.0, v225
	v_add_f32_e32 v226, 1.0, v226
	v_add_f32_e32 v227, 1.0, v227
	v_rcp_f32_e32 v224, v224
	v_rcp_f32_e32 v225, v225
	v_rcp_f32_e32 v226, v226
	v_rcp_f32_e32 v227, v227
	v_mul_f32_e32 v190, v224, v190
	v_mul_f32_e32 v191, v225, v191
	v_mul_f32_e32 v192, v226, v192
	v_mul_f32_e32 v193, v227, v193
	v_mul_f32_e32 v190, v100, v190
	v_mul_f32_e32 v191, v101, v191
	v_mul_f32_e32 v192, v102, v192
	v_mul_f32_e32 v193, v103, v193
	v_lshlrev_b32_e32 v194, 16, v132
	v_and_b32_e32 v195, 0xffff0000, v132
	v_lshlrev_b32_e32 v196, 16, v133
	v_and_b32_e32 v197, 0xffff0000, v133
	v_mul_f32_e32 v224, 0xbfb8aa3b, v194
	v_mul_f32_e32 v225, 0xbfb8aa3b, v195
	v_mul_f32_e32 v226, 0xbfb8aa3b, v196
	v_mul_f32_e32 v227, 0xbfb8aa3b, v197
	v_exp_f32_e32 v224, v224
	v_exp_f32_e32 v225, v225
	v_exp_f32_e32 v226, v226
	v_exp_f32_e32 v227, v227
	v_add_f32_e32 v224, 1.0, v224
	v_add_f32_e32 v225, 1.0, v225
	v_add_f32_e32 v226, 1.0, v226
	v_add_f32_e32 v227, 1.0, v227
	v_rcp_f32_e32 v224, v224
	v_rcp_f32_e32 v225, v225
	v_rcp_f32_e32 v226, v226
	v_rcp_f32_e32 v227, v227
	v_mul_f32_e32 v194, v224, v194
	v_mul_f32_e32 v195, v225, v195
	v_mul_f32_e32 v196, v226, v196
	v_mul_f32_e32 v197, v227, v197
	v_mul_f32_e32 v194, v104, v194
	v_mul_f32_e32 v195, v105, v195
	v_mul_f32_e32 v196, v106, v196
	v_mul_f32_e32 v197, v107, v197
	v_lshlrev_b32_e32 v198, 16, v134
	v_and_b32_e32 v199, 0xffff0000, v134
	v_lshlrev_b32_e32 v200, 16, v135
	v_and_b32_e32 v201, 0xffff0000, v135
	v_mul_f32_e32 v224, 0xbfb8aa3b, v198
	v_mul_f32_e32 v225, 0xbfb8aa3b, v199
	v_mul_f32_e32 v226, 0xbfb8aa3b, v200
	v_mul_f32_e32 v227, 0xbfb8aa3b, v201
	v_exp_f32_e32 v224, v224
	v_exp_f32_e32 v225, v225
	v_exp_f32_e32 v226, v226
	v_exp_f32_e32 v227, v227
	v_add_f32_e32 v224, 1.0, v224
	v_add_f32_e32 v225, 1.0, v225
	v_add_f32_e32 v226, 1.0, v226
	v_add_f32_e32 v227, 1.0, v227
	v_rcp_f32_e32 v224, v224
	v_rcp_f32_e32 v225, v225
	v_rcp_f32_e32 v226, v226
	v_rcp_f32_e32 v227, v227
	v_mul_f32_e32 v198, v224, v198
	v_mul_f32_e32 v199, v225, v199
	v_mul_f32_e32 v200, v226, v200
	v_mul_f32_e32 v201, v227, v201
	v_mul_f32_e32 v198, v108, v198
	v_mul_f32_e32 v199, v109, v199
	v_mul_f32_e32 v200, v110, v200
	v_mul_f32_e32 v201, v111, v201
	v_lshlrev_b32_e32 v202, 16, v136
	v_and_b32_e32 v203, 0xffff0000, v136
	v_lshlrev_b32_e32 v204, 16, v137
	v_and_b32_e32 v205, 0xffff0000, v137
	v_mul_f32_e32 v224, 0xbfb8aa3b, v202
	v_mul_f32_e32 v225, 0xbfb8aa3b, v203
	v_mul_f32_e32 v226, 0xbfb8aa3b, v204
	v_mul_f32_e32 v227, 0xbfb8aa3b, v205
	v_exp_f32_e32 v224, v224
	v_exp_f32_e32 v225, v225
	v_exp_f32_e32 v226, v226
	v_exp_f32_e32 v227, v227
	v_add_f32_e32 v224, 1.0, v224
	v_add_f32_e32 v225, 1.0, v225
	v_add_f32_e32 v226, 1.0, v226
	v_add_f32_e32 v227, 1.0, v227
	v_rcp_f32_e32 v224, v224
	v_rcp_f32_e32 v225, v225
	v_rcp_f32_e32 v226, v226
	v_rcp_f32_e32 v227, v227
	v_mul_f32_e32 v202, v224, v202
	v_mul_f32_e32 v203, v225, v203
	v_mul_f32_e32 v204, v226, v204
	v_mul_f32_e32 v205, v227, v205
	v_mul_f32_e32 v202, v112, v202
	v_mul_f32_e32 v203, v113, v203
	v_mul_f32_e32 v204, v114, v204
	v_mul_f32_e32 v205, v115, v205
	v_lshlrev_b32_e32 v206, 16, v138
	v_and_b32_e32 v207, 0xffff0000, v138
	v_lshlrev_b32_e32 v208, 16, v139
	v_and_b32_e32 v209, 0xffff0000, v139
	v_mul_f32_e32 v224, 0xbfb8aa3b, v206
	v_mul_f32_e32 v225, 0xbfb8aa3b, v207
	v_mul_f32_e32 v226, 0xbfb8aa3b, v208
	v_mul_f32_e32 v227, 0xbfb8aa3b, v209
	v_exp_f32_e32 v224, v224
	v_exp_f32_e32 v225, v225
	v_exp_f32_e32 v226, v226
	v_exp_f32_e32 v227, v227
	v_add_f32_e32 v224, 1.0, v224
	v_add_f32_e32 v225, 1.0, v225
	v_add_f32_e32 v226, 1.0, v226
	v_add_f32_e32 v227, 1.0, v227
	v_rcp_f32_e32 v224, v224
	v_rcp_f32_e32 v225, v225
	v_rcp_f32_e32 v226, v226
	v_rcp_f32_e32 v227, v227
	v_mul_f32_e32 v206, v224, v206
	v_mul_f32_e32 v207, v225, v207
	v_mul_f32_e32 v208, v226, v208
	v_mul_f32_e32 v209, v227, v209
	v_mul_f32_e32 v206, v116, v206
	v_mul_f32_e32 v207, v117, v207
	v_mul_f32_e32 v208, v118, v208
	v_mul_f32_e32 v209, v119, v209
	v_lshlrev_b32_e32 v210, 16, v140
	v_and_b32_e32 v211, 0xffff0000, v140
	v_lshlrev_b32_e32 v212, 16, v141
	v_and_b32_e32 v213, 0xffff0000, v141
	v_mul_f32_e32 v224, 0xbfb8aa3b, v210
	v_mul_f32_e32 v225, 0xbfb8aa3b, v211
	v_mul_f32_e32 v226, 0xbfb8aa3b, v212
	v_mul_f32_e32 v227, 0xbfb8aa3b, v213
	v_exp_f32_e32 v224, v224
	v_exp_f32_e32 v225, v225
	v_exp_f32_e32 v226, v226
	v_exp_f32_e32 v227, v227
	v_add_f32_e32 v224, 1.0, v224
	v_add_f32_e32 v225, 1.0, v225
	v_add_f32_e32 v226, 1.0, v226
	v_add_f32_e32 v227, 1.0, v227
	v_rcp_f32_e32 v224, v224
	v_rcp_f32_e32 v225, v225
	v_rcp_f32_e32 v226, v226
	v_rcp_f32_e32 v227, v227
	v_mul_f32_e32 v210, v224, v210
	v_mul_f32_e32 v211, v225, v211
	v_mul_f32_e32 v212, v226, v212
	v_mul_f32_e32 v213, v227, v213
	v_mul_f32_e32 v210, v120, v210
	v_mul_f32_e32 v211, v121, v211
	v_mul_f32_e32 v212, v122, v212
	v_mul_f32_e32 v213, v123, v213
	v_lshlrev_b32_e32 v214, 16, v142
	v_and_b32_e32 v215, 0xffff0000, v142
	v_lshlrev_b32_e32 v216, 16, v143
	v_and_b32_e32 v217, 0xffff0000, v143
	v_mul_f32_e32 v224, 0xbfb8aa3b, v214
	v_mul_f32_e32 v225, 0xbfb8aa3b, v215
	v_mul_f32_e32 v226, 0xbfb8aa3b, v216
	v_mul_f32_e32 v227, 0xbfb8aa3b, v217
	v_exp_f32_e32 v224, v224
	v_exp_f32_e32 v225, v225
	v_exp_f32_e32 v226, v226
	v_exp_f32_e32 v227, v227
	v_add_f32_e32 v224, 1.0, v224
	v_add_f32_e32 v225, 1.0, v225
	v_add_f32_e32 v226, 1.0, v226
	v_add_f32_e32 v227, 1.0, v227
	v_rcp_f32_e32 v224, v224
	v_rcp_f32_e32 v225, v225
	v_rcp_f32_e32 v226, v226
	v_rcp_f32_e32 v227, v227
	v_mul_f32_e32 v214, v224, v214
	v_mul_f32_e32 v215, v225, v215
	v_mul_f32_e32 v216, v226, v216
	v_mul_f32_e32 v217, v227, v217
	v_mul_f32_e32 v214, v124, v214
	v_mul_f32_e32 v215, v125, v215
	v_mul_f32_e32 v216, v126, v216
	v_mul_f32_e32 v217, v127, v217
	v_cvt_pk_bf16_f32 v96, v186, v187
	v_cvt_pk_bf16_f32 v97, v188, v189
	v_cvt_pk_bf16_f32 v98, v190, v191
	v_cvt_pk_bf16_f32 v99, v192, v193
	v_cvt_pk_bf16_f32 v100, v194, v195
	v_cvt_pk_bf16_f32 v101, v196, v197
	v_cvt_pk_bf16_f32 v102, v198, v199
	v_cvt_pk_bf16_f32 v103, v200, v201
	v_cvt_pk_bf16_f32 v104, v202, v203
	v_cvt_pk_bf16_f32 v105, v204, v205
	v_cvt_pk_bf16_f32 v106, v206, v207
	v_cvt_pk_bf16_f32 v107, v208, v209
	v_cvt_pk_bf16_f32 v108, v210, v211
	v_cvt_pk_bf16_f32 v109, v212, v213
	v_cvt_pk_bf16_f32 v110, v214, v215
	v_cvt_pk_bf16_f32 v111, v216, v217
	global_store_dwordx4 v[90:91], v[96:99], off offset:0
	global_store_dwordx4 v[90:91], v[100:103], off offset:16
	global_store_dwordx4 v[90:91], v[104:107], off offset:32
	global_store_dwordx4 v[90:91], v[108:111], off offset:48
	ds_write_b32 v85, v16
	ds_write_b32 v85, v17 offset:272
	ds_write_b32 v85, v18 offset:544
	ds_write_b32 v85, v19 offset:816
	ds_write_b32 v85, v20 offset:2176
	ds_write_b32 v85, v21 offset:2448
	ds_write_b32 v85, v22 offset:2720
	ds_write_b32 v85, v23 offset:2992
	ds_write_b32 v85, v24 offset:4352
	ds_write_b32 v85, v25 offset:4624
	ds_write_b32 v85, v26 offset:4896
	ds_write_b32 v85, v27 offset:5168
	ds_write_b32 v85, v28 offset:6528
	ds_write_b32 v85, v29 offset:6800
	ds_write_b32 v85, v30 offset:7072
	ds_write_b32 v85, v31 offset:7344
	ds_write_b32 v85, v0 offset:128
	ds_write_b32 v85, v1 offset:400
	ds_write_b32 v85, v2 offset:672
	ds_write_b32 v85, v3 offset:944
	ds_write_b32 v85, v4 offset:2304
	ds_write_b32 v85, v5 offset:2576
	ds_write_b32 v85, v6 offset:2848
	ds_write_b32 v85, v7 offset:3120
	ds_write_b32 v85, v8 offset:4480
	ds_write_b32 v85, v9 offset:4752
	ds_write_b32 v85, v10 offset:5024
	ds_write_b32 v85, v11 offset:5296
	ds_write_b32 v85, v12 offset:6656
	ds_write_b32 v85, v13 offset:6928
	ds_write_b32 v85, v14 offset:7200
	ds_write_b32 v85, v15 offset:7472
	s_waitcnt lgkmcnt(0)
	ds_read_b128 v[96:99], v86
	ds_read_b128 v[100:103], v86 offset:16
	ds_read_b128 v[104:107], v86 offset:32
	ds_read_b128 v[108:111], v86 offset:48
	ds_read_b128 v[112:115], v86 offset:64
	ds_read_b128 v[116:119], v86 offset:80
	ds_read_b128 v[120:123], v86 offset:96
	ds_read_b128 v[124:127], v86 offset:112
	s_waitcnt vmcnt(4) lgkmcnt(0)
	v_lshlrev_b32_e32 v186, 16, v144
	v_and_b32_e32 v187, 0xffff0000, v144
	v_lshlrev_b32_e32 v188, 16, v145
	v_and_b32_e32 v189, 0xffff0000, v145
	v_mul_f32_e32 v224, 0xbfb8aa3b, v186
	v_mul_f32_e32 v225, 0xbfb8aa3b, v187
	v_mul_f32_e32 v226, 0xbfb8aa3b, v188
	v_mul_f32_e32 v227, 0xbfb8aa3b, v189
	v_exp_f32_e32 v224, v224
	v_exp_f32_e32 v225, v225
	v_exp_f32_e32 v226, v226
	v_exp_f32_e32 v227, v227
	v_add_f32_e32 v224, 1.0, v224
	v_add_f32_e32 v225, 1.0, v225
	v_add_f32_e32 v226, 1.0, v226
	v_add_f32_e32 v227, 1.0, v227
	v_rcp_f32_e32 v224, v224
	v_rcp_f32_e32 v225, v225
	v_rcp_f32_e32 v226, v226
	v_rcp_f32_e32 v227, v227
	v_mul_f32_e32 v186, v224, v186
	v_mul_f32_e32 v187, v225, v187
	v_mul_f32_e32 v188, v226, v188
	v_mul_f32_e32 v189, v227, v189
	v_mul_f32_e32 v186, v96, v186
	v_mul_f32_e32 v187, v97, v187
	v_mul_f32_e32 v188, v98, v188
	v_mul_f32_e32 v189, v99, v189
	v_lshlrev_b32_e32 v190, 16, v146
	v_and_b32_e32 v191, 0xffff0000, v146
	v_lshlrev_b32_e32 v192, 16, v147
	v_and_b32_e32 v193, 0xffff0000, v147
	v_mul_f32_e32 v224, 0xbfb8aa3b, v190
	v_mul_f32_e32 v225, 0xbfb8aa3b, v191
	v_mul_f32_e32 v226, 0xbfb8aa3b, v192
	v_mul_f32_e32 v227, 0xbfb8aa3b, v193
	v_exp_f32_e32 v224, v224
	v_exp_f32_e32 v225, v225
	v_exp_f32_e32 v226, v226
	v_exp_f32_e32 v227, v227
	v_add_f32_e32 v224, 1.0, v224
	v_add_f32_e32 v225, 1.0, v225
	v_add_f32_e32 v226, 1.0, v226
	v_add_f32_e32 v227, 1.0, v227
	v_rcp_f32_e32 v224, v224
	v_rcp_f32_e32 v225, v225
	v_rcp_f32_e32 v226, v226
	v_rcp_f32_e32 v227, v227
	v_mul_f32_e32 v190, v224, v190
	v_mul_f32_e32 v191, v225, v191
	v_mul_f32_e32 v192, v226, v192
	v_mul_f32_e32 v193, v227, v193
	v_mul_f32_e32 v190, v100, v190
	v_mul_f32_e32 v191, v101, v191
	v_mul_f32_e32 v192, v102, v192
	v_mul_f32_e32 v193, v103, v193
	v_lshlrev_b32_e32 v194, 16, v148
	v_and_b32_e32 v195, 0xffff0000, v148
	v_lshlrev_b32_e32 v196, 16, v149
	v_and_b32_e32 v197, 0xffff0000, v149
	v_mul_f32_e32 v224, 0xbfb8aa3b, v194
	v_mul_f32_e32 v225, 0xbfb8aa3b, v195
	v_mul_f32_e32 v226, 0xbfb8aa3b, v196
	v_mul_f32_e32 v227, 0xbfb8aa3b, v197
	v_exp_f32_e32 v224, v224
	v_exp_f32_e32 v225, v225
	v_exp_f32_e32 v226, v226
	v_exp_f32_e32 v227, v227
	v_add_f32_e32 v224, 1.0, v224
	v_add_f32_e32 v225, 1.0, v225
	v_add_f32_e32 v226, 1.0, v226
	v_add_f32_e32 v227, 1.0, v227
	v_rcp_f32_e32 v224, v224
	v_rcp_f32_e32 v225, v225
	v_rcp_f32_e32 v226, v226
	v_rcp_f32_e32 v227, v227
	v_mul_f32_e32 v194, v224, v194
	v_mul_f32_e32 v195, v225, v195
	v_mul_f32_e32 v196, v226, v196
	v_mul_f32_e32 v197, v227, v197
	v_mul_f32_e32 v194, v104, v194
	v_mul_f32_e32 v195, v105, v195
	v_mul_f32_e32 v196, v106, v196
	v_mul_f32_e32 v197, v107, v197
	v_lshlrev_b32_e32 v198, 16, v150
	v_and_b32_e32 v199, 0xffff0000, v150
	v_lshlrev_b32_e32 v200, 16, v151
	v_and_b32_e32 v201, 0xffff0000, v151
	v_mul_f32_e32 v224, 0xbfb8aa3b, v198
	v_mul_f32_e32 v225, 0xbfb8aa3b, v199
	v_mul_f32_e32 v226, 0xbfb8aa3b, v200
	v_mul_f32_e32 v227, 0xbfb8aa3b, v201
	v_exp_f32_e32 v224, v224
	v_exp_f32_e32 v225, v225
	v_exp_f32_e32 v226, v226
	v_exp_f32_e32 v227, v227
	v_add_f32_e32 v224, 1.0, v224
	v_add_f32_e32 v225, 1.0, v225
	v_add_f32_e32 v226, 1.0, v226
	v_add_f32_e32 v227, 1.0, v227
	v_rcp_f32_e32 v224, v224
	v_rcp_f32_e32 v225, v225
	v_rcp_f32_e32 v226, v226
	v_rcp_f32_e32 v227, v227
	v_mul_f32_e32 v198, v224, v198
	v_mul_f32_e32 v199, v225, v199
	v_mul_f32_e32 v200, v226, v200
	v_mul_f32_e32 v201, v227, v201
	v_mul_f32_e32 v198, v108, v198
	v_mul_f32_e32 v199, v109, v199
	v_mul_f32_e32 v200, v110, v200
	v_mul_f32_e32 v201, v111, v201
	v_lshlrev_b32_e32 v202, 16, v152
	v_and_b32_e32 v203, 0xffff0000, v152
	v_lshlrev_b32_e32 v204, 16, v153
	v_and_b32_e32 v205, 0xffff0000, v153
	v_mul_f32_e32 v224, 0xbfb8aa3b, v202
	v_mul_f32_e32 v225, 0xbfb8aa3b, v203
	v_mul_f32_e32 v226, 0xbfb8aa3b, v204
	v_mul_f32_e32 v227, 0xbfb8aa3b, v205
	v_exp_f32_e32 v224, v224
	v_exp_f32_e32 v225, v225
	v_exp_f32_e32 v226, v226
	v_exp_f32_e32 v227, v227
	v_add_f32_e32 v224, 1.0, v224
	v_add_f32_e32 v225, 1.0, v225
	v_add_f32_e32 v226, 1.0, v226
	v_add_f32_e32 v227, 1.0, v227
	v_rcp_f32_e32 v224, v224
	v_rcp_f32_e32 v225, v225
	v_rcp_f32_e32 v226, v226
	v_rcp_f32_e32 v227, v227
	v_mul_f32_e32 v202, v224, v202
	v_mul_f32_e32 v203, v225, v203
	v_mul_f32_e32 v204, v226, v204
	v_mul_f32_e32 v205, v227, v205
	v_mul_f32_e32 v202, v112, v202
	v_mul_f32_e32 v203, v113, v203
	v_mul_f32_e32 v204, v114, v204
	v_mul_f32_e32 v205, v115, v205
	v_lshlrev_b32_e32 v206, 16, v154
	v_and_b32_e32 v207, 0xffff0000, v154
	v_lshlrev_b32_e32 v208, 16, v155
	v_and_b32_e32 v209, 0xffff0000, v155
	v_mul_f32_e32 v224, 0xbfb8aa3b, v206
	v_mul_f32_e32 v225, 0xbfb8aa3b, v207
	v_mul_f32_e32 v226, 0xbfb8aa3b, v208
	v_mul_f32_e32 v227, 0xbfb8aa3b, v209
	v_exp_f32_e32 v224, v224
	v_exp_f32_e32 v225, v225
	v_exp_f32_e32 v226, v226
	v_exp_f32_e32 v227, v227
	v_add_f32_e32 v224, 1.0, v224
	v_add_f32_e32 v225, 1.0, v225
	v_add_f32_e32 v226, 1.0, v226
	v_add_f32_e32 v227, 1.0, v227
	v_rcp_f32_e32 v224, v224
	v_rcp_f32_e32 v225, v225
	v_rcp_f32_e32 v226, v226
	v_rcp_f32_e32 v227, v227
	v_mul_f32_e32 v206, v224, v206
	v_mul_f32_e32 v207, v225, v207
	v_mul_f32_e32 v208, v226, v208
	v_mul_f32_e32 v209, v227, v209
	v_mul_f32_e32 v206, v116, v206
	v_mul_f32_e32 v207, v117, v207
	v_mul_f32_e32 v208, v118, v208
	v_mul_f32_e32 v209, v119, v209
	v_lshlrev_b32_e32 v210, 16, v156
	v_and_b32_e32 v211, 0xffff0000, v156
	v_lshlrev_b32_e32 v212, 16, v157
	v_and_b32_e32 v213, 0xffff0000, v157
	v_mul_f32_e32 v224, 0xbfb8aa3b, v210
	v_mul_f32_e32 v225, 0xbfb8aa3b, v211
	v_mul_f32_e32 v226, 0xbfb8aa3b, v212
	v_mul_f32_e32 v227, 0xbfb8aa3b, v213
	v_exp_f32_e32 v224, v224
	v_exp_f32_e32 v225, v225
	v_exp_f32_e32 v226, v226
	v_exp_f32_e32 v227, v227
	v_add_f32_e32 v224, 1.0, v224
	v_add_f32_e32 v225, 1.0, v225
	v_add_f32_e32 v226, 1.0, v226
	v_add_f32_e32 v227, 1.0, v227
	v_rcp_f32_e32 v224, v224
	v_rcp_f32_e32 v225, v225
	v_rcp_f32_e32 v226, v226
	v_rcp_f32_e32 v227, v227
	v_mul_f32_e32 v210, v224, v210
	v_mul_f32_e32 v211, v225, v211
	v_mul_f32_e32 v212, v226, v212
	v_mul_f32_e32 v213, v227, v213
	v_mul_f32_e32 v210, v120, v210
	v_mul_f32_e32 v211, v121, v211
	v_mul_f32_e32 v212, v122, v212
	v_mul_f32_e32 v213, v123, v213
	v_lshlrev_b32_e32 v214, 16, v158
	v_and_b32_e32 v215, 0xffff0000, v158
	v_lshlrev_b32_e32 v216, 16, v159
	v_and_b32_e32 v217, 0xffff0000, v159
	v_mul_f32_e32 v224, 0xbfb8aa3b, v214
	v_mul_f32_e32 v225, 0xbfb8aa3b, v215
	v_mul_f32_e32 v226, 0xbfb8aa3b, v216
	v_mul_f32_e32 v227, 0xbfb8aa3b, v217
	v_exp_f32_e32 v224, v224
	v_exp_f32_e32 v225, v225
	v_exp_f32_e32 v226, v226
	v_exp_f32_e32 v227, v227
	v_add_f32_e32 v224, 1.0, v224
	v_add_f32_e32 v225, 1.0, v225
	v_add_f32_e32 v226, 1.0, v226
	v_add_f32_e32 v227, 1.0, v227
	v_rcp_f32_e32 v224, v224
	v_rcp_f32_e32 v225, v225
	v_rcp_f32_e32 v226, v226
	v_rcp_f32_e32 v227, v227
	v_mul_f32_e32 v214, v224, v214
	v_mul_f32_e32 v215, v225, v215
	v_mul_f32_e32 v216, v226, v216
	v_mul_f32_e32 v217, v227, v217
	v_mul_f32_e32 v214, v124, v214
	v_mul_f32_e32 v215, v125, v215
	v_mul_f32_e32 v216, v126, v216
	v_mul_f32_e32 v217, v127, v217
	v_cvt_pk_bf16_f32 v96, v186, v187
	v_cvt_pk_bf16_f32 v97, v188, v189
	v_cvt_pk_bf16_f32 v98, v190, v191
	v_cvt_pk_bf16_f32 v99, v192, v193
	v_cvt_pk_bf16_f32 v100, v194, v195
	v_cvt_pk_bf16_f32 v101, v196, v197
	v_cvt_pk_bf16_f32 v102, v198, v199
	v_cvt_pk_bf16_f32 v103, v200, v201
	v_cvt_pk_bf16_f32 v104, v202, v203
	v_cvt_pk_bf16_f32 v105, v204, v205
	v_cvt_pk_bf16_f32 v106, v206, v207
	v_cvt_pk_bf16_f32 v107, v208, v209
	v_cvt_pk_bf16_f32 v108, v210, v211
	v_cvt_pk_bf16_f32 v109, v212, v213
	v_cvt_pk_bf16_f32 v110, v214, v215
	v_cvt_pk_bf16_f32 v111, v216, v217
	global_store_dwordx4 v[90:91], v[96:99], off offset:128
	global_store_dwordx4 v[90:91], v[100:103], off offset:144
	global_store_dwordx4 v[90:91], v[104:107], off offset:160
	global_store_dwordx4 v[90:91], v[108:111], off offset:176
	s_add_i32 s4, s35, 1
	s_cmp_lt_u32 s35, 2
	s_mov_b32 s35, s4
	s_cselect_b64 s[2:3], -1, 0
	s_and_b64 s[2:3], s[0:1], s[2:3]
	s_andn2_b64 vcc, exec, s[2:3]
	s_waitcnt vmcnt(63) expcnt(7) lgkmcnt(15)
	s_barrier
	s_cbranch_vccnz .LBB0_642

.LBB0_730:
	v_mov_b32_e32 v48, 0
	s_barrier
	s_mov_b64 s[2:3], exec
	v_readlane_b32 s12, v254, 9
	v_readlane_b32 s13, v254, 10
	s_and_b64 s[12:13], s[2:3], s[12:13]
	s_mov_b64 exec, s[12:13]
	s_cbranch_execz .LBB0_734
	s_mov_b64 s[14:15], exec
	v_mbcnt_lo_u32_b32 v0, s14, 0
	v_mbcnt_hi_u32_b32 v0, s15, v0
	v_cmp_eq_u32_e32 vcc, 0, v0
	s_and_saveexec_b64 s[12:13], vcc
	s_cbranch_execz .LBB0_733
	s_bcnt1_i32_b64 s14, s[14:15]
	v_readlane_b32 s52, v254, 0
	v_mov_b32_e32 v4, s14
	v_readlane_b32 s54, v254, 2
	v_readlane_b32 s55, v254, 3
	v_readlane_b32 s53, v254, 1
	v_readlane_b32 s56, v254, 4
	v_readlane_b32 s57, v254, 5
	v_readlane_b32 s58, v254, 6
	v_readlane_b32 s59, v254, 7
	global_atomic_add v48, v1, v4, s[54:55] sc0
.LBB0_733:
	s_or_b64 exec, exec, s[12:13]
.LBB0_734:
	s_or_b64 exec, exec, s[2:3]
	s_bfe_u32 s15, s0, 0x70003
	s_xor_b32 s2, s15, 64
	s_lshl_b32 s0, s0, 7
	s_and_b32 s0, s0, 0x380
	s_lshl_b32 s20, s2, 6
	v_mov_b32_e32 v12, v180
	s_cmp_lt_u32 s2, 64
	s_cselect_b64 s[12:13], -1, 0
	v_and_b32_e32 v0, 0x7f, v12
	s_cmp_gt_u32 s2, 63
	v_or_b32_e32 v5, s0, v0
	s_cselect_b64 s[2:3], -1, 0
	s_add_i32 s0, s20, 0xfffff000
	s_lshr_b32 s14, s0, 11
	v_mov_b32_e32 v7, 0
	s_and_b64 vcc, exec, s[12:13]
	v_lshlrev_b32_e32 v4, 2, v5
	v_mov_b32_e32 v6, 0
	s_cbranch_vccnz .LBB0_736
	s_lshl_b32 s0, s14, 2
	v_readlane_b32 s64, v254, 28
	s_lshl_b64 s[24:25], s[0:1], 12
	v_readlane_b32 s70, v254, 34
	v_readlane_b32 s71, v254, 35
	s_add_u32 s24, s70, s24
	s_addc_u32 s25, s71, s25
	global_load_dword v6, v4, s[24:25]
	v_readlane_b32 s65, v254, 29
	v_readlane_b32 s66, v254, 30
	v_readlane_b32 s67, v254, 31
	v_readlane_b32 s68, v254, 32
	v_readlane_b32 s69, v254, 33
	v_readlane_b32 s72, v254, 36
	v_readlane_b32 s73, v254, 37
	v_readlane_b32 s74, v254, 38
	v_readlane_b32 s75, v254, 39
	v_readlane_b32 s76, v254, 40
	v_readlane_b32 s77, v254, 41
	v_readlane_b32 s78, v254, 42
	v_readlane_b32 s79, v254, 43

.LBB0_1306:
	s_or_b64 exec, exec, s[2:3]
	v_readlane_b32 s64, v254, 12
	s_lshl_b64 s[2:3], s[8:9], 13
	v_readlane_b32 s72, v254, 20
	v_readlane_b32 s73, v254, 21
	s_add_u32 s2, s72, s2
	s_addc_u32 s3, s73, s3
	s_add_u32 s2, s2, s18
	s_addc_u32 s3, s3, s19
	s_lshl_b32 s4, s12, 8
	s_add_u32 s2, s2, s4
	v_readlane_b32 s70, v254, 18
	s_addc_u32 s3, s3, 0
	s_mul_i32 s6, s8, 0x5040
	v_readlane_b32 s71, v254, 19
	s_mul_hi_u32 s5, s8, 0x5040
	s_add_u32 s6, s70, s6
	s_addc_u32 s5, s71, s5
	s_add_u32 s6, s6, s14
	s_addc_u32 s5, s5, s15
	s_waitcnt lgkmcnt(0)
	v_add_u32_e32 v76, v179, v176
	v_mov_b32_e32 v80, v180
	s_add_u32 s4, s6, s4
	ds_read_b128 v[64:67], v76
	ds_read_b128 v[68:71], v76 offset:32
	ds_read_b128 v[72:75], v76 offset:64
	ds_read_b128 v[76:79], v76 offset:96
	s_addc_u32 s5, s5, 0
	v_and_b32_e32 v81, 31, v80
	v_bfe_u32 v82, v80, 5, 1
	v_lshrrev_b32_e32 v83, 6, v80
	v_and_b32_e32 v84, 63, v80
	v_lshrrev_b32_e32 v92, 1, v84
	v_and_b32_e32 v93, 1, v84
	v_lshl_add_u32 v94, v83, 5, v92
	v_mov_b64_e32 v[88:89], s[4:5]
	v_mad_i64_i32 v[88:89], s[6:7], v94, s52, v[88:89]
	v_lshlrev_b32_e32 v86, 6, v93
	v_mov_b32_e32 v87, 0
	v_lshl_add_u64 v[88:89], v[88:89], 0, v[86:87]
	global_load_dwordx4 v[128:131], v[88:89], off offset:0
	global_load_dwordx4 v[132:135], v[88:89], off offset:16
	global_load_dwordx4 v[136:139], v[88:89], off offset:32
	global_load_dwordx4 v[140:143], v[88:89], off offset:48
	global_load_dwordx4 v[144:147], v[88:89], off offset:128
	global_load_dwordx4 v[148:151], v[88:89], off offset:144
	global_load_dwordx4 v[152:155], v[88:89], off offset:160
	global_load_dwordx4 v[156:159], v[88:89], off offset:176
	v_mov_b32_e32 v95, 0
	v_lshlrev_b64 v[90:91], 13, v[94:95]
	v_lshl_add_u64 v[90:91], v[90:91], 0, s[2:3]
	v_lshl_add_u64 v[90:91], v[90:91], 0, v[86:87]
	v_mul_u32_u24_e32 v85, 0x2200, v83
	v_mul_u32_u24_e32 v86, 0x110, v92
	v_lshl_add_u32 v86, v93, 7, v86
	v_add_u32_e32 v86, v85, v86
	v_mul_u32_u24_e32 v87, 0x440, v82
	v_lshl_add_u32 v87, v81, 2, v87
	v_add_u32_e32 v85, v85, v87
	s_waitcnt lgkmcnt(0)
	v_rcp_f32_e32 v64, v64
	v_rcp_f32_e32 v65, v65
	v_rcp_f32_e32 v66, v66
	v_rcp_f32_e32 v67, v67
	v_rcp_f32_e32 v68, v68
	v_rcp_f32_e32 v69, v69
	v_rcp_f32_e32 v70, v70
	v_rcp_f32_e32 v71, v71
	v_rcp_f32_e32 v72, v72
	v_rcp_f32_e32 v73, v73
	v_rcp_f32_e32 v74, v74
	v_rcp_f32_e32 v75, v75
	v_rcp_f32_e32 v76, v76
	v_rcp_f32_e32 v77, v77
	v_rcp_f32_e32 v78, v78
	v_rcp_f32_e32 v79, v79
	v_mul_f32_e32 v0, v0, v64
	v_mul_f32_e32 v1, v1, v65
	v_mul_f32_e32 v2, v2, v66
	v_mul_f32_e32 v3, v3, v67
	v_mul_f32_e32 v4, v4, v68
	v_mul_f32_e32 v5, v5, v69
	v_mul_f32_e32 v6, v6, v70
	v_mul_f32_e32 v7, v7, v71
	v_mul_f32_e32 v8, v8, v72
	v_mul_f32_e32 v9, v9, v73
	v_mul_f32_e32 v10, v10, v74
	v_mul_f32_e32 v11, v11, v75
	v_mul_f32_e32 v12, v12, v76
	v_mul_f32_e32 v13, v13, v77
	v_mul_f32_e32 v14, v14, v78
	v_mul_f32_e32 v15, v15, v79
	v_mul_f32_e32 v16, v16, v64
	v_mul_f32_e32 v17, v17, v65
	v_mul_f32_e32 v18, v18, v66
	v_mul_f32_e32 v19, v19, v67
	v_mul_f32_e32 v20, v20, v68
	v_mul_f32_e32 v21, v21, v69
	v_mul_f32_e32 v22, v22, v70
	v_mul_f32_e32 v23, v23, v71
	v_mul_f32_e32 v24, v24, v72
	v_mul_f32_e32 v25, v25, v73
	v_mul_f32_e32 v26, v26, v74
	v_mul_f32_e32 v27, v27, v75
	v_mul_f32_e32 v28, v28, v76
	v_mul_f32_e32 v29, v29, v77
	v_mul_f32_e32 v30, v30, v78
	v_mul_f32_e32 v31, v31, v79
	v_mul_f32_e32 v32, v32, v64
	v_mul_f32_e32 v33, v33, v65
	v_mul_f32_e32 v34, v34, v66
	v_mul_f32_e32 v35, v35, v67
	v_mul_f32_e32 v36, v36, v68
	v_mul_f32_e32 v37, v37, v69
	v_mul_f32_e32 v38, v38, v70
	v_mul_f32_e32 v39, v39, v71
	v_mul_f32_e32 v40, v40, v72
	v_mul_f32_e32 v41, v41, v73
	v_mul_f32_e32 v42, v42, v74
	v_mul_f32_e32 v43, v43, v75
	v_mul_f32_e32 v44, v44, v76
	v_mul_f32_e32 v45, v45, v77
	v_mul_f32_e32 v46, v46, v78
	v_mul_f32_e32 v47, v47, v79
	v_mul_f32_e32 v48, v48, v64
	v_mul_f32_e32 v49, v49, v65
	v_mul_f32_e32 v50, v50, v66
	v_mul_f32_e32 v51, v51, v67
	v_mul_f32_e32 v52, v52, v68
	v_mul_f32_e32 v53, v53, v69
	v_mul_f32_e32 v54, v54, v70
	v_mul_f32_e32 v55, v55, v71
	v_mul_f32_e32 v56, v56, v72
	v_mul_f32_e32 v57, v57, v73
	v_mul_f32_e32 v58, v58, v74
	v_mul_f32_e32 v59, v59, v75
	v_mul_f32_e32 v60, v60, v76
	v_mul_f32_e32 v61, v61, v77
	v_mul_f32_e32 v62, v62, v78
	v_mul_f32_e32 v63, v63, v79
	s_barrier
	ds_write_b32 v85, v48
	ds_write_b32 v85, v49 offset:272
	ds_write_b32 v85, v50 offset:544
	ds_write_b32 v85, v51 offset:816
	ds_write_b32 v85, v52 offset:2176
	ds_write_b32 v85, v53 offset:2448
	ds_write_b32 v85, v54 offset:2720
	ds_write_b32 v85, v55 offset:2992
	ds_write_b32 v85, v56 offset:4352
	ds_write_b32 v85, v57 offset:4624
	ds_write_b32 v85, v58 offset:4896
	ds_write_b32 v85, v59 offset:5168
	ds_write_b32 v85, v60 offset:6528
	ds_write_b32 v85, v61 offset:6800
	ds_write_b32 v85, v62 offset:7072
	ds_write_b32 v85, v63 offset:7344
	ds_write_b32 v85, v32 offset:128
	ds_write_b32 v85, v33 offset:400
	ds_write_b32 v85, v34 offset:672
	ds_write_b32 v85, v35 offset:944
	ds_write_b32 v85, v36 offset:2304
	ds_write_b32 v85, v37 offset:2576
	ds_write_b32 v85, v38 offset:2848
	ds_write_b32 v85, v39 offset:3120
	ds_write_b32 v85, v40 offset:4480
	ds_write_b32 v85, v41 offset:4752
	ds_write_b32 v85, v42 offset:5024
	ds_write_b32 v85, v43 offset:5296
	ds_write_b32 v85, v44 offset:6656
	ds_write_b32 v85, v45 offset:6928
	ds_write_b32 v85, v46 offset:7200
	ds_write_b32 v85, v47 offset:7472
	s_waitcnt lgkmcnt(0)
	ds_read_b128 v[96:99], v86
	ds_read_b128 v[100:103], v86 offset:16
	ds_read_b128 v[104:107], v86 offset:32
	ds_read_b128 v[108:111], v86 offset:48
	ds_read_b128 v[112:115], v86 offset:64
	ds_read_b128 v[116:119], v86 offset:80
	ds_read_b128 v[120:123], v86 offset:96
	ds_read_b128 v[124:127], v86 offset:112
	s_waitcnt vmcnt(4) lgkmcnt(0)
	v_lshlrev_b32_e32 v186, 16, v128
	v_and_b32_e32 v187, 0xffff0000, v128
	v_lshlrev_b32_e32 v188, 16, v129
	v_and_b32_e32 v189, 0xffff0000, v129
	v_mul_f32_e32 v224, 0xbfb8aa3b, v186
	v_mul_f32_e32 v225, 0xbfb8aa3b, v187
	v_mul_f32_e32 v226, 0xbfb8aa3b, v188
	v_mul_f32_e32 v227, 0xbfb8aa3b, v189
	v_exp_f32_e32 v224, v224
	v_exp_f32_e32 v225, v225
	v_exp_f32_e32 v226, v226
	v_exp_f32_e32 v227, v227
	v_add_f32_e32 v224, 1.0, v224
	v_add_f32_e32 v225, 1.0, v225
	v_add_f32_e32 v226, 1.0, v226
	v_add_f32_e32 v227, 1.0, v227
	v_rcp_f32_e32 v224, v224
	v_rcp_f32_e32 v225, v225
	v_rcp_f32_e32 v226, v226
	v_rcp_f32_e32 v227, v227
	v_mul_f32_e32 v186, v224, v186
	v_mul_f32_e32 v187, v225, v187
	v_mul_f32_e32 v188, v226, v188
	v_mul_f32_e32 v189, v227, v189
	v_mul_f32_e32 v186, v96, v186
	v_mul_f32_e32 v187, v97, v187
	v_mul_f32_e32 v188, v98, v188
	v_mul_f32_e32 v189, v99, v189
	v_lshlrev_b32_e32 v190, 16, v130
	v_and_b32_e32 v191, 0xffff0000, v130
	v_lshlrev_b32_e32 v192, 16, v131
	v_and_b32_e32 v193, 0xffff0000, v131
	v_mul_f32_e32 v224, 0xbfb8aa3b, v190
	v_mul_f32_e32 v225, 0xbfb8aa3b, v191
	v_mul_f32_e32 v226, 0xbfb8aa3b, v192
	v_mul_f32_e32 v227, 0xbfb8aa3b, v193
	v_exp_f32_e32 v224, v224
	v_exp_f32_e32 v225, v225
	v_exp_f32_e32 v226, v226
	v_exp_f32_e32 v227, v227
	v_add_f32_e32 v224, 1.0, v224
	v_add_f32_e32 v225, 1.0, v225
	v_add_f32_e32 v226, 1.0, v226
	v_add_f32_e32 v227, 1.0, v227
	v_rcp_f32_e32 v224, v224
	v_rcp_f32_e32 v225, v225
	v_rcp_f32_e32 v226, v226
	v_rcp_f32_e32 v227, v227
	v_mul_f32_e32 v190, v224, v190
	v_mul_f32_e32 v191, v225, v191
	v_mul_f32_e32 v192, v226, v192
	v_mul_f32_e32 v193, v227, v193
	v_mul_f32_e32 v190, v100, v190
	v_mul_f32_e32 v191, v101, v191
	v_mul_f32_e32 v192, v102, v192
	v_mul_f32_e32 v193, v103, v193
	v_lshlrev_b32_e32 v194, 16, v132
	v_and_b32_e32 v195, 0xffff0000, v132
	v_lshlrev_b32_e32 v196, 16, v133
	v_and_b32_e32 v197, 0xffff0000, v133
	v_mul_f32_e32 v224, 0xbfb8aa3b, v194
	v_mul_f32_e32 v225, 0xbfb8aa3b, v195
	v_mul_f32_e32 v226, 0xbfb8aa3b, v196
	v_mul_f32_e32 v227, 0xbfb8aa3b, v197
	v_exp_f32_e32 v224, v224
	v_exp_f32_e32 v225, v225
	v_exp_f32_e32 v226, v226
	v_exp_f32_e32 v227, v227
	v_add_f32_e32 v224, 1.0, v224
	v_add_f32_e32 v225, 1.0, v225
	v_add_f32_e32 v226, 1.0, v226
	v_add_f32_e32 v227, 1.0, v227
	v_rcp_f32_e32 v224, v224
	v_rcp_f32_e32 v225, v225
	v_rcp_f32_e32 v226, v226
	v_rcp_f32_e32 v227, v227
	v_mul_f32_e32 v194, v224, v194
	v_mul_f32_e32 v195, v225, v195
	v_mul_f32_e32 v196, v226, v196
	v_mul_f32_e32 v197, v227, v197
	v_mul_f32_e32 v194, v104, v194
	v_mul_f32_e32 v195, v105, v195
	v_mul_f32_e32 v196, v106, v196
	v_mul_f32_e32 v197, v107, v197
	v_lshlrev_b32_e32 v198, 16, v134
	v_and_b32_e32 v199, 0xffff0000, v134
	v_lshlrev_b32_e32 v200, 16, v135
	v_and_b32_e32 v201, 0xffff0000, v135
	v_mul_f32_e32 v224, 0xbfb8aa3b, v198
	v_mul_f32_e32 v225, 0xbfb8aa3b, v199
	v_mul_f32_e32 v226, 0xbfb8aa3b, v200
	v_mul_f32_e32 v227, 0xbfb8aa3b, v201
	v_exp_f32_e32 v224, v224
	v_exp_f32_e32 v225, v225
	v_exp_f32_e32 v226, v226
	v_exp_f32_e32 v227, v227
	v_add_f32_e32 v224, 1.0, v224
	v_add_f32_e32 v225, 1.0, v225
	v_add_f32_e32 v226, 1.0, v226
	v_add_f32_e32 v227, 1.0, v227
	v_rcp_f32_e32 v224, v224
	v_rcp_f32_e32 v225, v225
	v_rcp_f32_e32 v226, v226
	v_rcp_f32_e32 v227, v227
	v_mul_f32_e32 v198, v224, v198
	v_mul_f32_e32 v199, v225, v199
	v_mul_f32_e32 v200, v226, v200
	v_mul_f32_e32 v201, v227, v201
	v_mul_f32_e32 v198, v108, v198
	v_mul_f32_e32 v199, v109, v199
	v_mul_f32_e32 v200, v110, v200
	v_mul_f32_e32 v201, v111, v201
	v_lshlrev_b32_e32 v202, 16, v136
	v_and_b32_e32 v203, 0xffff0000, v136
	v_lshlrev_b32_e32 v204, 16, v137
	v_and_b32_e32 v205, 0xffff0000, v137
	v_mul_f32_e32 v224, 0xbfb8aa3b, v202
	v_mul_f32_e32 v225, 0xbfb8aa3b, v203
	v_mul_f32_e32 v226, 0xbfb8aa3b, v204
	v_mul_f32_e32 v227, 0xbfb8aa3b, v205
	v_exp_f32_e32 v224, v224
	v_exp_f32_e32 v225, v225
	v_exp_f32_e32 v226, v226
	v_exp_f32_e32 v227, v227
	v_add_f32_e32 v224, 1.0, v224
	v_add_f32_e32 v225, 1.0, v225
	v_add_f32_e32 v226, 1.0, v226
	v_add_f32_e32 v227, 1.0, v227
	v_rcp_f32_e32 v224, v224
	v_rcp_f32_e32 v225, v225
	v_rcp_f32_e32 v226, v226
	v_rcp_f32_e32 v227, v227
	v_mul_f32_e32 v202, v224, v202
	v_mul_f32_e32 v203, v225, v203
	v_mul_f32_e32 v204, v226, v204
	v_mul_f32_e32 v205, v227, v205
	v_mul_f32_e32 v202, v112, v202
	v_mul_f32_e32 v203, v113, v203
	v_mul_f32_e32 v204, v114, v204
	v_mul_f32_e32 v205, v115, v205
	v_lshlrev_b32_e32 v206, 16, v138
	v_and_b32_e32 v207, 0xffff0000, v138
	v_lshlrev_b32_e32 v208, 16, v139
	v_and_b32_e32 v209, 0xffff0000, v139
	v_mul_f32_e32 v224, 0xbfb8aa3b, v206
	v_mul_f32_e32 v225, 0xbfb8aa3b, v207
	v_mul_f32_e32 v226, 0xbfb8aa3b, v208
	v_mul_f32_e32 v227, 0xbfb8aa3b, v209
	v_exp_f32_e32 v224, v224
	v_exp_f32_e32 v225, v225
	v_exp_f32_e32 v226, v226
	v_exp_f32_e32 v227, v227
	v_add_f32_e32 v224, 1.0, v224
	v_add_f32_e32 v225, 1.0, v225
	v_add_f32_e32 v226, 1.0, v226
	v_add_f32_e32 v227, 1.0, v227
	v_rcp_f32_e32 v224, v224
	v_rcp_f32_e32 v225, v225
	v_rcp_f32_e32 v226, v226
	v_rcp_f32_e32 v227, v227
	v_mul_f32_e32 v206, v224, v206
	v_mul_f32_e32 v207, v225, v207
	v_mul_f32_e32 v208, v226, v208
	v_mul_f32_e32 v209, v227, v209
	v_mul_f32_e32 v206, v116, v206
	v_mul_f32_e32 v207, v117, v207
	v_mul_f32_e32 v208, v118, v208
	v_mul_f32_e32 v209, v119, v209
	v_lshlrev_b32_e32 v210, 16, v140
	v_and_b32_e32 v211, 0xffff0000, v140
	v_lshlrev_b32_e32 v212, 16, v141
	v_and_b32_e32 v213, 0xffff0000, v141
	v_mul_f32_e32 v224, 0xbfb8aa3b, v210
	v_mul_f32_e32 v225, 0xbfb8aa3b, v211
	v_mul_f32_e32 v226, 0xbfb8aa3b, v212
	v_mul_f32_e32 v227, 0xbfb8aa3b, v213
	v_exp_f32_e32 v224, v224
	v_exp_f32_e32 v225, v225
	v_exp_f32_e32 v226, v226
	v_exp_f32_e32 v227, v227
	v_add_f32_e32 v224, 1.0, v224
	v_add_f32_e32 v225, 1.0, v225
	v_add_f32_e32 v226, 1.0, v226
	v_add_f32_e32 v227, 1.0, v227
	v_rcp_f32_e32 v224, v224
	v_rcp_f32_e32 v225, v225
	v_rcp_f32_e32 v226, v226
	v_rcp_f32_e32 v227, v227
	v_mul_f32_e32 v210, v224, v210
	v_mul_f32_e32 v211, v225, v211
	v_mul_f32_e32 v212, v226, v212
	v_mul_f32_e32 v213, v227, v213
	v_mul_f32_e32 v210, v120, v210
	v_mul_f32_e32 v211, v121, v211
	v_mul_f32_e32 v212, v122, v212
	v_mul_f32_e32 v213, v123, v213
	v_lshlrev_b32_e32 v214, 16, v142
	v_and_b32_e32 v215, 0xffff0000, v142
	v_lshlrev_b32_e32 v216, 16, v143
	v_and_b32_e32 v217, 0xffff0000, v143
	v_mul_f32_e32 v224, 0xbfb8aa3b, v214
	v_mul_f32_e32 v225, 0xbfb8aa3b, v215
	v_mul_f32_e32 v226, 0xbfb8aa3b, v216
	v_mul_f32_e32 v227, 0xbfb8aa3b, v217
	v_exp_f32_e32 v224, v224
	v_exp_f32_e32 v225, v225
	v_exp_f32_e32 v226, v226
	v_exp_f32_e32 v227, v227
	v_add_f32_e32 v224, 1.0, v224
	v_add_f32_e32 v225, 1.0, v225
	v_add_f32_e32 v226, 1.0, v226
	v_add_f32_e32 v227, 1.0, v227
	v_rcp_f32_e32 v224, v224
	v_rcp_f32_e32 v225, v225
	v_rcp_f32_e32 v226, v226
	v_rcp_f32_e32 v227, v227
	v_mul_f32_e32 v214, v224, v214
	v_mul_f32_e32 v215, v225, v215
	v_mul_f32_e32 v216, v226, v216
	v_mul_f32_e32 v217, v227, v217
	v_mul_f32_e32 v214, v124, v214
	v_mul_f32_e32 v215, v125, v215
	v_mul_f32_e32 v216, v126, v216
	v_mul_f32_e32 v217, v127, v217
	v_cvt_pk_bf16_f32 v96, v186, v187
	v_cvt_pk_bf16_f32 v97, v188, v189
	v_cvt_pk_bf16_f32 v98, v190, v191
	v_cvt_pk_bf16_f32 v99, v192, v193
	v_cvt_pk_bf16_f32 v100, v194, v195
	v_cvt_pk_bf16_f32 v101, v196, v197
	v_cvt_pk_bf16_f32 v102, v198, v199
	v_cvt_pk_bf16_f32 v103, v200, v201
	v_cvt_pk_bf16_f32 v104, v202, v203
	v_cvt_pk_bf16_f32 v105, v204, v205
	v_cvt_pk_bf16_f32 v106, v206, v207
	v_cvt_pk_bf16_f32 v107, v208, v209
	v_cvt_pk_bf16_f32 v108, v210, v211
	v_cvt_pk_bf16_f32 v109, v212, v213
	v_cvt_pk_bf16_f32 v110, v214, v215
	v_cvt_pk_bf16_f32 v111, v216, v217
	global_store_dwordx4 v[90:91], v[96:99], off offset:0
	global_store_dwordx4 v[90:91], v[100:103], off offset:16
	global_store_dwordx4 v[90:91], v[104:107], off offset:32
	global_store_dwordx4 v[90:91], v[108:111], off offset:48
	ds_write_b32 v85, v16
	ds_write_b32 v85, v17 offset:272
	ds_write_b32 v85, v18 offset:544
	ds_write_b32 v85, v19 offset:816
	ds_write_b32 v85, v20 offset:2176
	ds_write_b32 v85, v21 offset:2448
	ds_write_b32 v85, v22 offset:2720
	ds_write_b32 v85, v23 offset:2992
	ds_write_b32 v85, v24 offset:4352
	ds_write_b32 v85, v25 offset:4624
	ds_write_b32 v85, v26 offset:4896
	ds_write_b32 v85, v27 offset:5168
	ds_write_b32 v85, v28 offset:6528
	ds_write_b32 v85, v29 offset:6800
	ds_write_b32 v85, v30 offset:7072
	ds_write_b32 v85, v31 offset:7344
	ds_write_b32 v85, v0 offset:128
	ds_write_b32 v85, v1 offset:400
	ds_write_b32 v85, v2 offset:672
	ds_write_b32 v85, v3 offset:944
	ds_write_b32 v85, v4 offset:2304
	ds_write_b32 v85, v5 offset:2576
	ds_write_b32 v85, v6 offset:2848
	ds_write_b32 v85, v7 offset:3120
	ds_write_b32 v85, v8 offset:4480
	ds_write_b32 v85, v9 offset:4752
	ds_write_b32 v85, v10 offset:5024
	ds_write_b32 v85, v11 offset:5296
	ds_write_b32 v85, v12 offset:6656
	ds_write_b32 v85, v13 offset:6928
	ds_write_b32 v85, v14 offset:7200
	ds_write_b32 v85, v15 offset:7472
	s_waitcnt lgkmcnt(0)
	ds_read_b128 v[96:99], v86
	ds_read_b128 v[100:103], v86 offset:16
	ds_read_b128 v[104:107], v86 offset:32
	ds_read_b128 v[108:111], v86 offset:48
	ds_read_b128 v[112:115], v86 offset:64
	ds_read_b128 v[116:119], v86 offset:80
	ds_read_b128 v[120:123], v86 offset:96
	ds_read_b128 v[124:127], v86 offset:112
	s_waitcnt vmcnt(4) lgkmcnt(0)
	v_lshlrev_b32_e32 v186, 16, v144
	v_and_b32_e32 v187, 0xffff0000, v144
	v_lshlrev_b32_e32 v188, 16, v145
	v_and_b32_e32 v189, 0xffff0000, v145
	v_mul_f32_e32 v224, 0xbfb8aa3b, v186
	v_mul_f32_e32 v225, 0xbfb8aa3b, v187
	v_mul_f32_e32 v226, 0xbfb8aa3b, v188
	v_mul_f32_e32 v227, 0xbfb8aa3b, v189
	v_exp_f32_e32 v224, v224
	v_exp_f32_e32 v225, v225
	v_exp_f32_e32 v226, v226
	v_exp_f32_e32 v227, v227
	v_add_f32_e32 v224, 1.0, v224
	v_add_f32_e32 v225, 1.0, v225
	v_add_f32_e32 v226, 1.0, v226
	v_add_f32_e32 v227, 1.0, v227
	v_rcp_f32_e32 v224, v224
	v_rcp_f32_e32 v225, v225
	v_rcp_f32_e32 v226, v226
	v_rcp_f32_e32 v227, v227
	v_mul_f32_e32 v186, v224, v186
	v_mul_f32_e32 v187, v225, v187
	v_mul_f32_e32 v188, v226, v188
	v_mul_f32_e32 v189, v227, v189
	v_mul_f32_e32 v186, v96, v186
	v_mul_f32_e32 v187, v97, v187
	v_mul_f32_e32 v188, v98, v188
	v_mul_f32_e32 v189, v99, v189
	v_lshlrev_b32_e32 v190, 16, v146
	v_and_b32_e32 v191, 0xffff0000, v146
	v_lshlrev_b32_e32 v192, 16, v147
	v_and_b32_e32 v193, 0xffff0000, v147
	v_mul_f32_e32 v224, 0xbfb8aa3b, v190
	v_mul_f32_e32 v225, 0xbfb8aa3b, v191
	v_mul_f32_e32 v226, 0xbfb8aa3b, v192
	v_mul_f32_e32 v227, 0xbfb8aa3b, v193
	v_exp_f32_e32 v224, v224
	v_exp_f32_e32 v225, v225
	v_exp_f32_e32 v226, v226
	v_exp_f32_e32 v227, v227
	v_add_f32_e32 v224, 1.0, v224
	v_add_f32_e32 v225, 1.0, v225
	v_add_f32_e32 v226, 1.0, v226
	v_add_f32_e32 v227, 1.0, v227
	v_rcp_f32_e32 v224, v224
	v_rcp_f32_e32 v225, v225
	v_rcp_f32_e32 v226, v226
	v_rcp_f32_e32 v227, v227
	v_mul_f32_e32 v190, v224, v190
	v_mul_f32_e32 v191, v225, v191
	v_mul_f32_e32 v192, v226, v192
	v_mul_f32_e32 v193, v227, v193
	v_mul_f32_e32 v190, v100, v190
	v_mul_f32_e32 v191, v101, v191
	v_mul_f32_e32 v192, v102, v192
	v_mul_f32_e32 v193, v103, v193
	v_lshlrev_b32_e32 v194, 16, v148
	v_and_b32_e32 v195, 0xffff0000, v148
	v_lshlrev_b32_e32 v196, 16, v149
	v_and_b32_e32 v197, 0xffff0000, v149
	v_mul_f32_e32 v224, 0xbfb8aa3b, v194
	v_mul_f32_e32 v225, 0xbfb8aa3b, v195
	v_mul_f32_e32 v226, 0xbfb8aa3b, v196
	v_mul_f32_e32 v227, 0xbfb8aa3b, v197
	v_exp_f32_e32 v224, v224
	v_exp_f32_e32 v225, v225
	v_exp_f32_e32 v226, v226
	v_exp_f32_e32 v227, v227
	v_add_f32_e32 v224, 1.0, v224
	v_add_f32_e32 v225, 1.0, v225
	v_add_f32_e32 v226, 1.0, v226
	v_add_f32_e32 v227, 1.0, v227
	v_rcp_f32_e32 v224, v224
	v_rcp_f32_e32 v225, v225
	v_rcp_f32_e32 v226, v226
	v_rcp_f32_e32 v227, v227
	v_mul_f32_e32 v194, v224, v194
	v_mul_f32_e32 v195, v225, v195
	v_mul_f32_e32 v196, v226, v196
	v_mul_f32_e32 v197, v227, v197
	v_mul_f32_e32 v194, v104, v194
	v_mul_f32_e32 v195, v105, v195
	v_mul_f32_e32 v196, v106, v196
	v_mul_f32_e32 v197, v107, v197
	v_lshlrev_b32_e32 v198, 16, v150
	v_and_b32_e32 v199, 0xffff0000, v150
	v_lshlrev_b32_e32 v200, 16, v151
	v_and_b32_e32 v201, 0xffff0000, v151
	v_mul_f32_e32 v224, 0xbfb8aa3b, v198
	v_mul_f32_e32 v225, 0xbfb8aa3b, v199
	v_mul_f32_e32 v226, 0xbfb8aa3b, v200
	v_mul_f32_e32 v227, 0xbfb8aa3b, v201
	v_exp_f32_e32 v224, v224
	v_exp_f32_e32 v225, v225
	v_exp_f32_e32 v226, v226
	v_exp_f32_e32 v227, v227
	v_add_f32_e32 v224, 1.0, v224
	v_add_f32_e32 v225, 1.0, v225
	v_add_f32_e32 v226, 1.0, v226
	v_add_f32_e32 v227, 1.0, v227
	v_rcp_f32_e32 v224, v224
	v_rcp_f32_e32 v225, v225
	v_rcp_f32_e32 v226, v226
	v_rcp_f32_e32 v227, v227
	v_mul_f32_e32 v198, v224, v198
	v_mul_f32_e32 v199, v225, v199
	v_mul_f32_e32 v200, v226, v200
	v_mul_f32_e32 v201, v227, v201
	v_mul_f32_e32 v198, v108, v198
	v_mul_f32_e32 v199, v109, v199
	v_mul_f32_e32 v200, v110, v200
	v_mul_f32_e32 v201, v111, v201
	v_lshlrev_b32_e32 v202, 16, v152
	v_and_b32_e32 v203, 0xffff0000, v152
	v_lshlrev_b32_e32 v204, 16, v153
	v_and_b32_e32 v205, 0xffff0000, v153
	v_mul_f32_e32 v224, 0xbfb8aa3b, v202
	v_mul_f32_e32 v225, 0xbfb8aa3b, v203
	v_mul_f32_e32 v226, 0xbfb8aa3b, v204
	v_mul_f32_e32 v227, 0xbfb8aa3b, v205
	v_exp_f32_e32 v224, v224
	v_exp_f32_e32 v225, v225
	v_exp_f32_e32 v226, v226
	v_exp_f32_e32 v227, v227
	v_add_f32_e32 v224, 1.0, v224
	v_add_f32_e32 v225, 1.0, v225
	v_add_f32_e32 v226, 1.0, v226
	v_add_f32_e32 v227, 1.0, v227
	v_rcp_f32_e32 v224, v224
	v_rcp_f32_e32 v225, v225
	v_rcp_f32_e32 v226, v226
	v_rcp_f32_e32 v227, v227
	v_mul_f32_e32 v202, v224, v202
	v_mul_f32_e32 v203, v225, v203
	v_mul_f32_e32 v204, v226, v204
	v_mul_f32_e32 v205, v227, v205
	v_mul_f32_e32 v202, v112, v202
	v_mul_f32_e32 v203, v113, v203
	v_mul_f32_e32 v204, v114, v204
	v_mul_f32_e32 v205, v115, v205
	v_lshlrev_b32_e32 v206, 16, v154
	v_and_b32_e32 v207, 0xffff0000, v154
	v_lshlrev_b32_e32 v208, 16, v155
	v_and_b32_e32 v209, 0xffff0000, v155
	v_mul_f32_e32 v224, 0xbfb8aa3b, v206
	v_mul_f32_e32 v225, 0xbfb8aa3b, v207
	v_mul_f32_e32 v226, 0xbfb8aa3b, v208
	v_mul_f32_e32 v227, 0xbfb8aa3b, v209
	v_exp_f32_e32 v224, v224
	v_exp_f32_e32 v225, v225
	v_exp_f32_e32 v226, v226
	v_exp_f32_e32 v227, v227
	v_add_f32_e32 v224, 1.0, v224
	v_add_f32_e32 v225, 1.0, v225
	v_add_f32_e32 v226, 1.0, v226
	v_add_f32_e32 v227, 1.0, v227
	v_rcp_f32_e32 v224, v224
	v_rcp_f32_e32 v225, v225
	v_rcp_f32_e32 v226, v226
	v_rcp_f32_e32 v227, v227
	v_mul_f32_e32 v206, v224, v206
	v_mul_f32_e32 v207, v225, v207
	v_mul_f32_e32 v208, v226, v208
	v_mul_f32_e32 v209, v227, v209
	v_mul_f32_e32 v206, v116, v206
	v_mul_f32_e32 v207, v117, v207
	v_mul_f32_e32 v208, v118, v208
	v_mul_f32_e32 v209, v119, v209
	v_lshlrev_b32_e32 v210, 16, v156
	v_and_b32_e32 v211, 0xffff0000, v156
	v_lshlrev_b32_e32 v212, 16, v157
	v_and_b32_e32 v213, 0xffff0000, v157
	v_mul_f32_e32 v224, 0xbfb8aa3b, v210
	v_mul_f32_e32 v225, 0xbfb8aa3b, v211
	v_mul_f32_e32 v226, 0xbfb8aa3b, v212
	v_mul_f32_e32 v227, 0xbfb8aa3b, v213
	v_exp_f32_e32 v224, v224
	v_exp_f32_e32 v225, v225
	v_exp_f32_e32 v226, v226
	v_exp_f32_e32 v227, v227
	v_add_f32_e32 v224, 1.0, v224
	v_add_f32_e32 v225, 1.0, v225
	v_add_f32_e32 v226, 1.0, v226
	v_add_f32_e32 v227, 1.0, v227
	v_rcp_f32_e32 v224, v224
	v_rcp_f32_e32 v225, v225
	v_rcp_f32_e32 v226, v226
	v_rcp_f32_e32 v227, v227
	v_mul_f32_e32 v210, v224, v210
	v_mul_f32_e32 v211, v225, v211
	v_mul_f32_e32 v212, v226, v212
	v_mul_f32_e32 v213, v227, v213
	v_mul_f32_e32 v210, v120, v210
	v_mul_f32_e32 v211, v121, v211
	v_mul_f32_e32 v212, v122, v212
	v_mul_f32_e32 v213, v123, v213
	v_lshlrev_b32_e32 v214, 16, v158
	v_and_b32_e32 v215, 0xffff0000, v158
	v_lshlrev_b32_e32 v216, 16, v159
	v_and_b32_e32 v217, 0xffff0000, v159
	v_mul_f32_e32 v224, 0xbfb8aa3b, v214
	v_mul_f32_e32 v225, 0xbfb8aa3b, v215
	v_mul_f32_e32 v226, 0xbfb8aa3b, v216
	v_mul_f32_e32 v227, 0xbfb8aa3b, v217
	v_exp_f32_e32 v224, v224
	v_exp_f32_e32 v225, v225
	v_exp_f32_e32 v226, v226
	v_exp_f32_e32 v227, v227
	v_add_f32_e32 v224, 1.0, v224
	v_add_f32_e32 v225, 1.0, v225
	v_add_f32_e32 v226, 1.0, v226
	v_add_f32_e32 v227, 1.0, v227
	v_rcp_f32_e32 v224, v224
	v_rcp_f32_e32 v225, v225
	v_rcp_f32_e32 v226, v226
	v_rcp_f32_e32 v227, v227
	v_mul_f32_e32 v214, v224, v214
	v_mul_f32_e32 v215, v225, v215
	v_mul_f32_e32 v216, v226, v216
	v_mul_f32_e32 v217, v227, v217
	v_mul_f32_e32 v214, v124, v214
	v_mul_f32_e32 v215, v125, v215
	v_mul_f32_e32 v216, v126, v216
	v_mul_f32_e32 v217, v127, v217
	v_cvt_pk_bf16_f32 v96, v186, v187
	v_cvt_pk_bf16_f32 v97, v188, v189
	v_cvt_pk_bf16_f32 v98, v190, v191
	v_cvt_pk_bf16_f32 v99, v192, v193
	v_cvt_pk_bf16_f32 v100, v194, v195
	v_cvt_pk_bf16_f32 v101, v196, v197
	v_cvt_pk_bf16_f32 v102, v198, v199
	v_cvt_pk_bf16_f32 v103, v200, v201
	v_cvt_pk_bf16_f32 v104, v202, v203
	v_cvt_pk_bf16_f32 v105, v204, v205
	v_cvt_pk_bf16_f32 v106, v206, v207
	v_cvt_pk_bf16_f32 v107, v208, v209
	v_cvt_pk_bf16_f32 v108, v210, v211
	v_cvt_pk_bf16_f32 v109, v212, v213
	v_cvt_pk_bf16_f32 v110, v214, v215
	v_cvt_pk_bf16_f32 v111, v216, v217
	global_store_dwordx4 v[90:91], v[96:99], off offset:128
	global_store_dwordx4 v[90:91], v[100:103], off offset:144
	global_store_dwordx4 v[90:91], v[104:107], off offset:160
	global_store_dwordx4 v[90:91], v[108:111], off offset:176
	s_add_i32 s4, s62, 1
	s_cmp_lt_u32 s62, 2
	s_mov_b32 s62, s4
	s_cselect_b64 s[2:3], -1, 0
	s_and_b64 s[2:3], s[0:1], s[2:3]
	s_andn2_b64 vcc, exec, s[2:3]
	s_waitcnt vmcnt(63) expcnt(7) lgkmcnt(15)
	s_barrier
	s_cbranch_vccnz .LBB0_1353

.LBB0_1441:
	v_mov_b32_e32 v48, 0
	s_barrier
	s_mov_b64 s[0:1], exec
	v_readlane_b32 s4, v254, 9
	v_readlane_b32 s5, v254, 10
	s_and_b64 s[4:5], s[0:1], s[4:5]
	s_mov_b64 exec, s[4:5]
	s_cbranch_execz .LBB0_1445
	s_mov_b64 s[6:7], exec
	v_mbcnt_lo_u32_b32 v0, s6, 0
	v_mbcnt_hi_u32_b32 v0, s7, v0
	v_cmp_eq_u32_e32 vcc, 0, v0
	s_and_saveexec_b64 s[4:5], vcc
	s_cbranch_execz .LBB0_1444
	s_bcnt1_i32_b64 s6, s[6:7]
	v_readlane_b32 s8, v254, 0
	v_mov_b32_e32 v4, s6
	v_readlane_b32 s10, v254, 2
	v_readlane_b32 s11, v254, 3
	v_readlane_b32 s9, v254, 1
	v_readlane_b32 s12, v254, 4
	v_readlane_b32 s13, v254, 5
	v_readlane_b32 s14, v254, 6
	v_readlane_b32 s15, v254, 7
	global_atomic_add v48, v1, v4, s[10:11] offset:4 sc0
.LBB0_1444:
	s_or_b64 exec, exec, s[4:5]
.LBB0_1445:
	s_or_b64 exec, exec, s[0:1]
	s_bfe_u32 s30, s2, 0x70003
	s_xor_b32 s0, s30, 64
	s_lshl_b32 s1, s2, 7
	s_and_b32 s1, s1, 0x380
	s_lshl_b32 s33, s0, 6
	v_mov_b32_e32 v10, v180
	s_cmp_lt_u32 s0, 64
	s_cselect_b64 s[24:25], -1, 0
	v_and_b32_e32 v0, 0x7f, v10
	s_cmp_gt_u32 s0, 63
	v_or_b32_e32 v5, s1, v0
	s_cselect_b64 s[0:1], -1, 0
	s_add_i32 s2, s33, 0xfffff000
	s_lshr_b32 s4, s2, 11
	v_mov_b32_e32 v7, 0
	s_and_b64 vcc, exec, s[24:25]
	v_lshlrev_b32_e32 v4, 2, v5
	v_mov_b32_e32 v6, 0
	s_cbranch_vccnz .LBB0_1447
	s_lshl_b32 s2, s4, 2
	v_readlane_b32 s56, v254, 28
	s_or_b32 s2, s2, 2
	v_readlane_b32 s62, v254, 34
	v_readlane_b32 s63, v254, 35
	s_lshl_b64 s[6:7], s[2:3], 12
	s_mov_b64 s[10:11], s[62:63]
	s_add_u32 s6, s10, s6
	s_addc_u32 s7, s11, s7
	global_load_dword v6, v4, s[6:7]
	v_readlane_b32 s57, v254, 29
	v_readlane_b32 s58, v254, 30
	v_readlane_b32 s59, v254, 31
	v_readlane_b32 s60, v254, 32
	v_readlane_b32 s61, v254, 33
	v_readlane_b32 s64, v254, 36
	v_readlane_b32 s65, v254, 37
	v_readlane_b32 s66, v254, 38
	v_readlane_b32 s67, v254, 39
	v_readlane_b32 s68, v254, 40
	v_readlane_b32 s69, v254, 41
	v_readlane_b32 s70, v254, 42
	v_readlane_b32 s71, v254, 43
